# v148 plus merged vmcnt(8)/lgkmcnt(0) waits and m0-write hoisted above address calc to drop 22 s_nop in GEMM K-loops
# baseline (speedup 1.0000x reference)
.LBB0_182:
	s_add_u32 s3, s4, 0xfffc0080
	s_addc_u32 s28, s5, -1
	s_add_i32 s46, 0, 0x10000
	s_cmp_eq_u32 s41, 12
	s_cselect_b32 s31, s0, s28
	s_cselect_b32 s30, s1, s3
	s_cselect_b32 s29, s10, s40
	s_cselect_b32 s28, s16, s17
	s_add_i32 s3, 0, 0x14000
	v_add_u32_e32 v144, s46, v229
	v_add_u32_e32 v170, s3, v229
	ds_read_b128 v[132:135], v144
	ds_read_b128 v[136:139], v144 offset:1024
	ds_read_b128 v[140:143], v144 offset:2048
	ds_read_b128 v[144:147], v144 offset:3072
	ds_read_b128 v[158:161], v170
	ds_read_b128 v[162:165], v170 offset:1024
	ds_read_b128 v[166:169], v170 offset:2048
	ds_read_b128 v[170:173], v170 offset:3072
	v_lshl_add_u64 v[178:179], s[4:5], 0, v[152:153]
	s_add_i32 m0, s95, 0xc000
	ds_read_b128 v[174:177], v230
	ds_read_b128 v[190:193], v230 offset:1024
	ds_read_b128 v[194:197], v230 offset:2048
	ds_read_b128 v[198:201], v230 offset:3072
	ds_read_b128 v[202:205], v230 offset:4096
	ds_read_b128 v[206:209], v230 offset:5120
	ds_read_b128 v[210:213], v230 offset:6144
	ds_read_b128 v[214:217], v230 offset:7168
	global_load_lds_dwordx4 v[178:179], off
	s_add_i32 m0, s95, 0xe000
	v_lshl_add_u64 v[178:179], s[4:5], 0, v[154:155]
	global_load_lds_dwordx4 v[178:179], off
	s_waitcnt vmcnt(8) lgkmcnt(0)
	s_barrier
	s_setprio 1
	v_mfma_f32_16x16x32_bf16 v[128:131], v[132:135], v[174:177], v[128:131]
	v_mfma_f32_16x16x32_bf16 v[124:127], v[140:143], v[174:177], v[124:127]
	v_mfma_f32_16x16x32_bf16 v[112:115], v[132:135], v[194:197], v[112:115]
	v_mfma_f32_16x16x32_bf16 v[108:111], v[140:143], v[194:197], v[108:111]
	v_mfma_f32_16x16x32_bf16 v[96:99], v[132:135], v[202:205], v[96:99]
	v_mfma_f32_16x16x32_bf16 v[92:95], v[140:143], v[202:205], v[92:95]
	v_mfma_f32_16x16x32_bf16 v[80:83], v[132:135], v[210:213], v[80:83]
	v_mfma_f32_16x16x32_bf16 v[76:79], v[140:143], v[210:213], v[76:79]
	v_mfma_f32_16x16x32_bf16 v[128:131], v[136:139], v[190:193], v[128:131]
	v_mfma_f32_16x16x32_bf16 v[124:127], v[144:147], v[190:193], v[124:127]
	v_mfma_f32_16x16x32_bf16 v[112:115], v[136:139], v[198:201], v[112:115]
	v_mfma_f32_16x16x32_bf16 v[108:111], v[144:147], v[198:201], v[108:111]
	v_mfma_f32_16x16x32_bf16 v[96:99], v[136:139], v[206:209], v[96:99]
	v_mfma_f32_16x16x32_bf16 v[92:95], v[144:147], v[206:209], v[92:95]
	v_mfma_f32_16x16x32_bf16 v[80:83], v[136:139], v[214:217], v[80:83]
	v_mfma_f32_16x16x32_bf16 v[76:79], v[144:147], v[214:217], v[76:79]
	v_mfma_f32_16x16x32_bf16 v[120:123], v[158:161], v[174:177], v[120:123]
	v_mfma_f32_16x16x32_bf16 v[116:119], v[166:169], v[174:177], v[116:119]
	v_mfma_f32_16x16x32_bf16 v[104:107], v[158:161], v[194:197], v[104:107]
	v_mfma_f32_16x16x32_bf16 v[100:103], v[166:169], v[194:197], v[100:103]
	v_mfma_f32_16x16x32_bf16 v[88:91], v[158:161], v[202:205], v[88:91]
	v_mfma_f32_16x16x32_bf16 v[84:87], v[166:169], v[202:205], v[84:87]
	v_mfma_f32_16x16x32_bf16 v[72:75], v[158:161], v[210:213], v[72:75]
	v_mfma_f32_16x16x32_bf16 v[68:71], v[166:169], v[210:213], v[68:71]
	v_mfma_f32_16x16x32_bf16 v[120:123], v[162:165], v[190:193], v[120:123]
	v_mfma_f32_16x16x32_bf16 v[116:119], v[170:173], v[190:193], v[116:119]
	v_mfma_f32_16x16x32_bf16 v[104:107], v[162:165], v[198:201], v[104:107]
	v_mfma_f32_16x16x32_bf16 v[100:103], v[170:173], v[198:201], v[100:103]
	v_mfma_f32_16x16x32_bf16 v[88:91], v[162:165], v[206:209], v[88:91]
	v_mfma_f32_16x16x32_bf16 v[84:87], v[170:173], v[206:209], v[84:87]
	v_mfma_f32_16x16x32_bf16 v[72:75], v[162:165], v[214:217], v[72:75]
	v_mfma_f32_16x16x32_bf16 v[68:71], v[170:173], v[214:217], v[68:71]
	s_setprio 0
	s_barrier
	s_add_i32 s46, s46, s99
	v_lshl_add_u64 v[178:179], s[28:29], 0, v[148:149]
	s_mov_b32 m0, s46
	ds_read_b128 v[174:177], v230 offset:16384
	ds_read_b128 v[190:193], v230 offset:17408
	ds_read_b128 v[194:197], v230 offset:18432
	ds_read_b128 v[198:201], v230 offset:19456
	ds_read_b128 v[202:205], v230 offset:20480
	ds_read_b128 v[206:209], v230 offset:21504
	ds_read_b128 v[210:213], v230 offset:22528
	ds_read_b128 v[214:217], v230 offset:23552
	global_load_lds_dwordx4 v[178:179], off
	s_add_i32 m0, s46, 0x2000
	s_add_u32 s46, s28, 0x40000
	v_lshl_add_u64 v[218:219], s[28:29], 0, v[150:151]
	s_addc_u32 s47, s29, 0
	s_add_i32 s3, s3, s99
	global_load_lds_dwordx4 v[218:219], off
	v_lshl_add_u64 v[232:233], s[46:47], 0, v[148:149]
	s_mov_b32 m0, s3
	v_lshl_add_u64 v[234:235], s[30:31], 0, v[150:151]
	global_load_lds_dwordx4 v[232:233], off
	s_add_i32 m0, s3, 0x2000
	v_lshl_add_u64 v[232:233], s[46:47], 0, v[150:151]
	global_load_lds_dwordx4 v[232:233], off
	s_mov_b32 m0, s95
	v_lshl_add_u64 v[232:233], s[30:31], 0, v[148:149]
	global_load_lds_dwordx4 v[232:233], off
	s_mov_b32 m0, s97
	s_nop 0
	global_load_lds_dwordx4 v[234:235], off
	s_waitcnt vmcnt(8) lgkmcnt(0)
	s_barrier
	s_setprio 1
	v_mfma_f32_16x16x32_bf16 v[62:65], v[132:135], v[174:177], v[62:65]
	v_mfma_f32_16x16x32_bf16 v[58:61], v[140:143], v[174:177], v[58:61]
	v_mfma_f32_16x16x32_bf16 v[46:49], v[132:135], v[194:197], v[46:49]
	v_mfma_f32_16x16x32_bf16 v[42:45], v[140:143], v[194:197], v[42:45]
	v_mfma_f32_16x16x32_bf16 v[30:33], v[132:135], v[202:205], v[30:33]
	v_mfma_f32_16x16x32_bf16 v[26:29], v[140:143], v[202:205], v[26:29]
	v_mfma_f32_16x16x32_bf16 v[14:17], v[132:135], v[210:213], v[14:17]
	v_mfma_f32_16x16x32_bf16 v[10:13], v[140:143], v[210:213], v[10:13]
	v_mfma_f32_16x16x32_bf16 v[62:65], v[136:139], v[190:193], v[62:65]
	v_mfma_f32_16x16x32_bf16 v[58:61], v[144:147], v[190:193], v[58:61]
	v_mfma_f32_16x16x32_bf16 v[46:49], v[136:139], v[198:201], v[46:49]
	v_mfma_f32_16x16x32_bf16 v[42:45], v[144:147], v[198:201], v[42:45]
	v_mfma_f32_16x16x32_bf16 v[30:33], v[136:139], v[206:209], v[30:33]
	v_mfma_f32_16x16x32_bf16 v[26:29], v[144:147], v[206:209], v[26:29]
	v_mfma_f32_16x16x32_bf16 v[14:17], v[136:139], v[214:217], v[14:17]
	v_mfma_f32_16x16x32_bf16 v[10:13], v[144:147], v[214:217], v[10:13]
	v_mfma_f32_16x16x32_bf16 v[54:57], v[158:161], v[174:177], v[54:57]
	v_mfma_f32_16x16x32_bf16 v[50:53], v[166:169], v[174:177], v[50:53]
	v_mfma_f32_16x16x32_bf16 v[38:41], v[158:161], v[194:197], v[38:41]
	v_mfma_f32_16x16x32_bf16 v[34:37], v[166:169], v[194:197], v[34:37]
	v_mfma_f32_16x16x32_bf16 v[22:25], v[158:161], v[202:205], v[22:25]
	v_mfma_f32_16x16x32_bf16 v[18:21], v[166:169], v[202:205], v[18:21]
	v_mfma_f32_16x16x32_bf16 v[6:9], v[158:161], v[210:213], v[6:9]
	v_mfma_f32_16x16x32_bf16 v[2:5], v[166:169], v[210:213], v[2:5]
	v_mfma_f32_16x16x32_bf16 v[54:57], v[162:165], v[190:193], v[54:57]
	v_mfma_f32_16x16x32_bf16 v[50:53], v[170:173], v[190:193], v[50:53]
	v_mfma_f32_16x16x32_bf16 v[38:41], v[162:165], v[198:201], v[38:41]
	v_mfma_f32_16x16x32_bf16 v[34:37], v[170:173], v[198:201], v[34:37]
	v_mfma_f32_16x16x32_bf16 v[22:25], v[162:165], v[206:209], v[22:25]
	v_mfma_f32_16x16x32_bf16 v[18:21], v[170:173], v[206:209], v[18:21]
	v_mfma_f32_16x16x32_bf16 v[6:9], v[162:165], v[214:217], v[6:9]
	v_mfma_f32_16x16x32_bf16 v[2:5], v[170:173], v[214:217], v[2:5]
	s_setprio 0
	s_barrier
	s_add_i32 s3, 0, 0x18000
	s_add_i32 s46, 0, 0x1c000
	v_add_u32_e32 v144, s3, v229
	v_add_u32_e32 v170, s46, v229
	ds_read_b128 v[132:135], v144
	ds_read_b128 v[136:139], v144 offset:1024
	ds_read_b128 v[140:143], v144 offset:2048
	ds_read_b128 v[144:147], v144 offset:3072
	ds_read_b128 v[158:161], v170
	ds_read_b128 v[162:165], v170 offset:1024
	ds_read_b128 v[166:169], v170 offset:2048
	ds_read_b128 v[170:173], v170 offset:3072
	s_add_u32 s30, s30, 0x40000
	s_addc_u32 s31, s31, 0
	s_mov_b32 m0, s49
	v_lshl_add_u64 v[236:237], s[30:31], 0, v[148:149]
	ds_read_b128 v[174:177], v230 offset:32768
	ds_read_b128 v[190:193], v230 offset:33792
	ds_read_b128 v[194:197], v230 offset:34816
	ds_read_b128 v[198:201], v230 offset:35840
	ds_read_b128 v[202:205], v230 offset:36864
	ds_read_b128 v[206:209], v230 offset:37888
	ds_read_b128 v[210:213], v230 offset:38912
	ds_read_b128 v[214:217], v230 offset:39936
	global_load_lds_dwordx4 v[236:237], off
	s_mov_b32 m0, s34
	v_lshl_add_u64 v[236:237], s[30:31], 0, v[150:151]
	global_load_lds_dwordx4 v[236:237], off
	s_waitcnt vmcnt(8) lgkmcnt(0)
	s_barrier
	s_setprio 1
	v_mfma_f32_16x16x32_bf16 v[128:131], v[132:135], v[174:177], v[128:131]
	v_mfma_f32_16x16x32_bf16 v[124:127], v[140:143], v[174:177], v[124:127]
	v_mfma_f32_16x16x32_bf16 v[112:115], v[132:135], v[194:197], v[112:115]
	v_mfma_f32_16x16x32_bf16 v[108:111], v[140:143], v[194:197], v[108:111]
	v_mfma_f32_16x16x32_bf16 v[96:99], v[132:135], v[202:205], v[96:99]
	v_mfma_f32_16x16x32_bf16 v[92:95], v[140:143], v[202:205], v[92:95]
	v_mfma_f32_16x16x32_bf16 v[80:83], v[132:135], v[210:213], v[80:83]
	v_mfma_f32_16x16x32_bf16 v[76:79], v[140:143], v[210:213], v[76:79]
	v_mfma_f32_16x16x32_bf16 v[128:131], v[136:139], v[190:193], v[128:131]
	v_mfma_f32_16x16x32_bf16 v[124:127], v[144:147], v[190:193], v[124:127]
	v_mfma_f32_16x16x32_bf16 v[112:115], v[136:139], v[198:201], v[112:115]
	v_mfma_f32_16x16x32_bf16 v[108:111], v[144:147], v[198:201], v[108:111]
	v_mfma_f32_16x16x32_bf16 v[96:99], v[136:139], v[206:209], v[96:99]
	v_mfma_f32_16x16x32_bf16 v[92:95], v[144:147], v[206:209], v[92:95]
	v_mfma_f32_16x16x32_bf16 v[80:83], v[136:139], v[214:217], v[80:83]
	v_mfma_f32_16x16x32_bf16 v[76:79], v[144:147], v[214:217], v[76:79]
	v_mfma_f32_16x16x32_bf16 v[120:123], v[158:161], v[174:177], v[120:123]
	v_mfma_f32_16x16x32_bf16 v[116:119], v[166:169], v[174:177], v[116:119]
	v_mfma_f32_16x16x32_bf16 v[104:107], v[158:161], v[194:197], v[104:107]
	v_mfma_f32_16x16x32_bf16 v[100:103], v[166:169], v[194:197], v[100:103]
	v_mfma_f32_16x16x32_bf16 v[88:91], v[158:161], v[202:205], v[88:91]
	v_mfma_f32_16x16x32_bf16 v[84:87], v[166:169], v[202:205], v[84:87]
	v_mfma_f32_16x16x32_bf16 v[72:75], v[158:161], v[210:213], v[72:75]
	v_mfma_f32_16x16x32_bf16 v[68:71], v[166:169], v[210:213], v[68:71]
	v_mfma_f32_16x16x32_bf16 v[120:123], v[162:165], v[190:193], v[120:123]
	v_mfma_f32_16x16x32_bf16 v[116:119], v[170:173], v[190:193], v[116:119]
	v_mfma_f32_16x16x32_bf16 v[104:107], v[162:165], v[198:201], v[104:107]
	v_mfma_f32_16x16x32_bf16 v[100:103], v[170:173], v[198:201], v[100:103]
	v_mfma_f32_16x16x32_bf16 v[88:91], v[162:165], v[206:209], v[88:91]
	v_mfma_f32_16x16x32_bf16 v[84:87], v[170:173], v[206:209], v[84:87]
	v_mfma_f32_16x16x32_bf16 v[72:75], v[162:165], v[214:217], v[72:75]
	v_mfma_f32_16x16x32_bf16 v[68:71], v[170:173], v[214:217], v[68:71]
	s_setprio 0
	s_barrier
	s_add_i32 s3, s3, s99
	v_lshl_add_u64 v[178:179], v[178:179], 0, s[18:19]
	s_mov_b32 m0, s3
	ds_read_b128 v[174:177], v230 offset:49152
	ds_read_b128 v[190:193], v230 offset:50176
	ds_read_b128 v[194:197], v230 offset:51200
	ds_read_b128 v[198:201], v230 offset:52224
	ds_read_b128 v[202:205], v230 offset:53248
	ds_read_b128 v[206:209], v230 offset:54272
	ds_read_b128 v[210:213], v230 offset:55296
	ds_read_b128 v[214:217], v230 offset:56320
	global_load_lds_dwordx4 v[178:179], off
	s_add_i32 m0, s3, 0x2000
	s_add_u32 s28, s28, 0x40080
	v_lshl_add_u64 v[178:179], v[218:219], 0, s[18:19]
	s_addc_u32 s29, s29, 0
	s_add_i32 s3, s46, s99
	global_load_lds_dwordx4 v[178:179], off
	s_mov_b32 m0, s3
	v_lshl_add_u64 v[178:179], s[28:29], 0, v[148:149]
	global_load_lds_dwordx4 v[178:179], off
	s_add_i32 m0, s3, 0x2000
	v_lshl_add_u64 v[178:179], s[28:29], 0, v[150:151]
	global_load_lds_dwordx4 v[178:179], off
	s_mov_b32 m0, s63
	v_lshl_add_u64 v[178:179], v[232:233], 0, s[18:19]
	global_load_lds_dwordx4 v[178:179], off
	s_mov_b32 m0, s11
	v_lshl_add_u64 v[178:179], v[234:235], 0, s[18:19]
	global_load_lds_dwordx4 v[178:179], off
	s_waitcnt vmcnt(8) lgkmcnt(0)
	s_barrier
	s_setprio 1
	v_mfma_f32_16x16x32_bf16 v[62:65], v[132:135], v[174:177], v[62:65]
	v_mfma_f32_16x16x32_bf16 v[58:61], v[140:143], v[174:177], v[58:61]
	v_mfma_f32_16x16x32_bf16 v[46:49], v[132:135], v[194:197], v[46:49]
	v_mfma_f32_16x16x32_bf16 v[42:45], v[140:143], v[194:197], v[42:45]
	v_mfma_f32_16x16x32_bf16 v[30:33], v[132:135], v[202:205], v[30:33]
	v_mfma_f32_16x16x32_bf16 v[26:29], v[140:143], v[202:205], v[26:29]
	v_mfma_f32_16x16x32_bf16 v[14:17], v[132:135], v[210:213], v[14:17]
	v_mfma_f32_16x16x32_bf16 v[10:13], v[140:143], v[210:213], v[10:13]
	v_mfma_f32_16x16x32_bf16 v[62:65], v[136:139], v[190:193], v[62:65]
	v_mfma_f32_16x16x32_bf16 v[58:61], v[144:147], v[190:193], v[58:61]
	v_mfma_f32_16x16x32_bf16 v[46:49], v[136:139], v[198:201], v[46:49]
	v_mfma_f32_16x16x32_bf16 v[42:45], v[144:147], v[198:201], v[42:45]
	v_mfma_f32_16x16x32_bf16 v[30:33], v[136:139], v[206:209], v[30:33]
	v_mfma_f32_16x16x32_bf16 v[26:29], v[144:147], v[206:209], v[26:29]
	v_mfma_f32_16x16x32_bf16 v[14:17], v[136:139], v[214:217], v[14:17]
	v_mfma_f32_16x16x32_bf16 v[10:13], v[144:147], v[214:217], v[10:13]
	v_mfma_f32_16x16x32_bf16 v[54:57], v[158:161], v[174:177], v[54:57]
	v_mfma_f32_16x16x32_bf16 v[50:53], v[166:169], v[174:177], v[50:53]
	v_mfma_f32_16x16x32_bf16 v[38:41], v[158:161], v[194:197], v[38:41]
	v_mfma_f32_16x16x32_bf16 v[34:37], v[166:169], v[194:197], v[34:37]
	v_mfma_f32_16x16x32_bf16 v[22:25], v[158:161], v[202:205], v[22:25]
	v_mfma_f32_16x16x32_bf16 v[18:21], v[166:169], v[202:205], v[18:21]
	v_mfma_f32_16x16x32_bf16 v[6:9], v[158:161], v[210:213], v[6:9]
	v_mfma_f32_16x16x32_bf16 v[2:5], v[166:169], v[210:213], v[2:5]
	v_mfma_f32_16x16x32_bf16 v[54:57], v[162:165], v[190:193], v[54:57]
	v_mfma_f32_16x16x32_bf16 v[50:53], v[170:173], v[190:193], v[50:53]
	v_mfma_f32_16x16x32_bf16 v[38:41], v[162:165], v[198:201], v[38:41]
	v_mfma_f32_16x16x32_bf16 v[34:37], v[170:173], v[198:201], v[34:37]
	v_mfma_f32_16x16x32_bf16 v[22:25], v[162:165], v[206:209], v[22:25]
	v_mfma_f32_16x16x32_bf16 v[18:21], v[170:173], v[206:209], v[18:21]
	v_mfma_f32_16x16x32_bf16 v[6:9], v[162:165], v[214:217], v[6:9]
	v_mfma_f32_16x16x32_bf16 v[2:5], v[170:173], v[214:217], v[2:5]
	s_setprio 0
	s_barrier
	s_add_i32 s41, s41, 2
	s_add_u32 s4, s4, 0x100
	s_addc_u32 s5, s5, 0
	s_add_u32 s17, s17, 0x100
	s_addc_u32 s40, s40, 0
	s_cmp_gt_u32 s41, 13
	s_cbranch_scc0 .LBB0_182
	s_and_b64 vcc, exec, s[6:7]
	s_movk_i32 s3, 0x2200
	s_mov_b32 s10, 0x22000
	s_mov_b32 s28, 0x24000
	s_mov_b32 s29, 0x26000
	s_mov_b32 s30, 0x28000
	s_mov_b32 s31, 0x44000
	s_mov_b32 s40, 0x46000
	s_mov_b32 s41, 0x48000
	s_mov_b32 s46, 0x4a000
	s_mov_b32 s47, 0x66000
	s_cbranch_vccz .LBB0_185
	s_barrier

.LBB0_290:
	s_add_i32 s47, s24, 2
	s_add_u32 s28, s4, 0x80
	s_addc_u32 s29, s5, 0
	s_add_i32 s3, 0, 0x10000
	s_cmp_eq_u32 s43, s24
	s_cselect_b32 s29, s97, s29
	s_cselect_b32 s28, s96, s28
	s_cselect_b32 vcc_hi, s99, s35
	s_cselect_b32 vcc_lo, s98, s34
	s_add_i32 s24, 0, 0x14000
	v_add_u32_e32 v150, s3, v165
	v_add_u32_e32 v162, s24, v165
	ds_read_b128 v[132:135], v150
	ds_read_b128 v[136:139], v150 offset:1024
	ds_read_b128 v[140:143], v150 offset:2048
	ds_read_b128 v[150:153], v150 offset:3072
	ds_read_b128 v[154:157], v162
	ds_read_b128 v[158:161], v162 offset:1024
	ds_read_b128 v[168:171], v162 offset:2048
	ds_read_b128 v[172:175], v162 offset:3072
	v_lshl_add_u64 v[162:163], s[4:5], 0, v[146:147]
	s_add_i32 m0, s63, 0xc000
	ds_read_b128 v[176:179], v166
	ds_read_b128 v[190:193], v166 offset:1024
	ds_read_b128 v[194:197], v166 offset:2048
	ds_read_b128 v[198:201], v166 offset:3072
	ds_read_b128 v[202:205], v166 offset:4096
	ds_read_b128 v[206:209], v166 offset:5120
	ds_read_b128 v[210:213], v166 offset:6144
	ds_read_b128 v[214:217], v166 offset:7168
	global_load_lds_dwordx4 v[162:163], off
	s_add_i32 m0, s63, 0xe000
	v_lshl_add_u64 v[162:163], s[4:5], 0, v[148:149]
	global_load_lds_dwordx4 v[162:163], off
	s_waitcnt vmcnt(8) lgkmcnt(0)
	s_barrier
	s_setprio 1
	v_mfma_f32_16x16x32_bf16 v[128:131], v[132:135], v[176:179], v[128:131]
	v_mfma_f32_16x16x32_bf16 v[124:127], v[140:143], v[176:179], v[124:127]
	v_mfma_f32_16x16x32_bf16 v[112:115], v[132:135], v[194:197], v[112:115]
	v_mfma_f32_16x16x32_bf16 v[108:111], v[140:143], v[194:197], v[108:111]
	v_mfma_f32_16x16x32_bf16 v[96:99], v[132:135], v[202:205], v[96:99]
	v_mfma_f32_16x16x32_bf16 v[92:95], v[140:143], v[202:205], v[92:95]
	v_mfma_f32_16x16x32_bf16 v[80:83], v[132:135], v[210:213], v[80:83]
	v_mfma_f32_16x16x32_bf16 v[76:79], v[140:143], v[210:213], v[76:79]
	v_mfma_f32_16x16x32_bf16 v[128:131], v[136:139], v[190:193], v[128:131]
	v_mfma_f32_16x16x32_bf16 v[124:127], v[150:153], v[190:193], v[124:127]
	v_mfma_f32_16x16x32_bf16 v[112:115], v[136:139], v[198:201], v[112:115]
	v_mfma_f32_16x16x32_bf16 v[108:111], v[150:153], v[198:201], v[108:111]
	v_mfma_f32_16x16x32_bf16 v[96:99], v[136:139], v[206:209], v[96:99]
	v_mfma_f32_16x16x32_bf16 v[92:95], v[150:153], v[206:209], v[92:95]
	v_mfma_f32_16x16x32_bf16 v[80:83], v[136:139], v[214:217], v[80:83]
	v_mfma_f32_16x16x32_bf16 v[76:79], v[150:153], v[214:217], v[76:79]
	v_mfma_f32_16x16x32_bf16 v[120:123], v[154:157], v[176:179], v[120:123]
	v_mfma_f32_16x16x32_bf16 v[116:119], v[168:171], v[176:179], v[116:119]
	v_mfma_f32_16x16x32_bf16 v[104:107], v[154:157], v[194:197], v[104:107]
	v_mfma_f32_16x16x32_bf16 v[100:103], v[168:171], v[194:197], v[100:103]
	v_mfma_f32_16x16x32_bf16 v[88:91], v[154:157], v[202:205], v[88:91]
	v_mfma_f32_16x16x32_bf16 v[84:87], v[168:171], v[202:205], v[84:87]
	v_mfma_f32_16x16x32_bf16 v[72:75], v[154:157], v[210:213], v[72:75]
	v_mfma_f32_16x16x32_bf16 v[68:71], v[168:171], v[210:213], v[68:71]
	v_mfma_f32_16x16x32_bf16 v[120:123], v[158:161], v[190:193], v[120:123]
	v_mfma_f32_16x16x32_bf16 v[116:119], v[172:175], v[190:193], v[116:119]
	v_mfma_f32_16x16x32_bf16 v[104:107], v[158:161], v[198:201], v[104:107]
	v_mfma_f32_16x16x32_bf16 v[100:103], v[172:175], v[198:201], v[100:103]
	v_mfma_f32_16x16x32_bf16 v[88:91], v[158:161], v[206:209], v[88:91]
	v_mfma_f32_16x16x32_bf16 v[84:87], v[172:175], v[206:209], v[84:87]
	v_mfma_f32_16x16x32_bf16 v[72:75], v[158:161], v[214:217], v[72:75]
	v_mfma_f32_16x16x32_bf16 v[68:71], v[172:175], v[214:217], v[68:71]
	s_setprio 0
	s_barrier
	s_add_i32 s3, s3, s56
	v_lshl_add_u64 v[162:163], vcc, 0, v[184:185]
	s_mov_b32 m0, s3
	ds_read_b128 v[176:179], v166 offset:16384
	ds_read_b128 v[190:193], v166 offset:17408
	ds_read_b128 v[194:197], v166 offset:18432
	ds_read_b128 v[198:201], v166 offset:19456
	ds_read_b128 v[202:205], v166 offset:20480
	ds_read_b128 v[206:209], v166 offset:21504
	ds_read_b128 v[210:213], v166 offset:22528
	ds_read_b128 v[214:217], v166 offset:23552
	global_load_lds_dwordx4 v[162:163], off
	s_add_i32 m0, s3, 0x2000
	v_lshl_add_u64 v[218:219], vcc, 0, v[144:145]
	s_add_u32 vcc_lo, vcc_lo, s78
	s_addc_u32 vcc_hi, vcc_hi, 0
	s_add_i32 s3, s24, s56
	global_load_lds_dwordx4 v[218:219], off
	v_lshl_add_u64 v[228:229], vcc, 0, v[184:185]
	s_mov_b32 m0, s3
	v_lshl_add_u64 v[230:231], vcc, 0, v[144:145]
	global_load_lds_dwordx4 v[228:229], off
	s_add_i32 m0, s3, 0x2000
	v_lshl_add_u64 v[232:233], s[28:29], 0, v[184:185]
	global_load_lds_dwordx4 v[230:231], off
	s_mov_b32 m0, s63
	v_lshl_add_u64 v[234:235], s[28:29], 0, v[144:145]
	global_load_lds_dwordx4 v[232:233], off
	s_mov_b32 m0, s55
	s_nop 0
	global_load_lds_dwordx4 v[234:235], off
	s_waitcnt vmcnt(8) lgkmcnt(0)
	s_barrier
	s_setprio 1
	v_mfma_f32_16x16x32_bf16 v[62:65], v[132:135], v[176:179], v[62:65]
	v_mfma_f32_16x16x32_bf16 v[58:61], v[140:143], v[176:179], v[58:61]
	v_mfma_f32_16x16x32_bf16 v[46:49], v[132:135], v[194:197], v[46:49]
	v_mfma_f32_16x16x32_bf16 v[42:45], v[140:143], v[194:197], v[42:45]
	v_mfma_f32_16x16x32_bf16 v[30:33], v[132:135], v[202:205], v[30:33]
	v_mfma_f32_16x16x32_bf16 v[26:29], v[140:143], v[202:205], v[26:29]
	v_mfma_f32_16x16x32_bf16 v[14:17], v[132:135], v[210:213], v[14:17]
	v_mfma_f32_16x16x32_bf16 v[10:13], v[140:143], v[210:213], v[10:13]
	v_mfma_f32_16x16x32_bf16 v[62:65], v[136:139], v[190:193], v[62:65]
	v_mfma_f32_16x16x32_bf16 v[58:61], v[150:153], v[190:193], v[58:61]
	v_mfma_f32_16x16x32_bf16 v[46:49], v[136:139], v[198:201], v[46:49]
	v_mfma_f32_16x16x32_bf16 v[42:45], v[150:153], v[198:201], v[42:45]
	v_mfma_f32_16x16x32_bf16 v[30:33], v[136:139], v[206:209], v[30:33]
	v_mfma_f32_16x16x32_bf16 v[26:29], v[150:153], v[206:209], v[26:29]
	v_mfma_f32_16x16x32_bf16 v[14:17], v[136:139], v[214:217], v[14:17]
	v_mfma_f32_16x16x32_bf16 v[10:13], v[150:153], v[214:217], v[10:13]
	v_mfma_f32_16x16x32_bf16 v[54:57], v[154:157], v[176:179], v[54:57]
	v_mfma_f32_16x16x32_bf16 v[50:53], v[168:171], v[176:179], v[50:53]
	v_mfma_f32_16x16x32_bf16 v[38:41], v[154:157], v[194:197], v[38:41]
	v_mfma_f32_16x16x32_bf16 v[34:37], v[168:171], v[194:197], v[34:37]
	v_mfma_f32_16x16x32_bf16 v[22:25], v[154:157], v[202:205], v[22:25]
	v_mfma_f32_16x16x32_bf16 v[18:21], v[168:171], v[202:205], v[18:21]
	v_mfma_f32_16x16x32_bf16 v[6:9], v[154:157], v[210:213], v[6:9]
	v_mfma_f32_16x16x32_bf16 v[2:5], v[168:171], v[210:213], v[2:5]
	v_mfma_f32_16x16x32_bf16 v[54:57], v[158:161], v[190:193], v[54:57]
	v_mfma_f32_16x16x32_bf16 v[50:53], v[172:175], v[190:193], v[50:53]
	v_mfma_f32_16x16x32_bf16 v[38:41], v[158:161], v[198:201], v[38:41]
	v_mfma_f32_16x16x32_bf16 v[34:37], v[172:175], v[198:201], v[34:37]
	v_mfma_f32_16x16x32_bf16 v[22:25], v[158:161], v[206:209], v[22:25]
	v_mfma_f32_16x16x32_bf16 v[18:21], v[172:175], v[206:209], v[18:21]
	v_mfma_f32_16x16x32_bf16 v[6:9], v[158:161], v[214:217], v[6:9]
	v_mfma_f32_16x16x32_bf16 v[2:5], v[172:175], v[214:217], v[2:5]
	s_setprio 0
	s_barrier
	s_add_i32 s3, 0, 0x18000
	s_add_i32 s24, 0, 0x1c000
	v_add_u32_e32 v150, s3, v165
	v_add_u32_e32 v167, s24, v165
	ds_read_b128 v[132:135], v150
	ds_read_b128 v[136:139], v150 offset:1024
	ds_read_b128 v[140:143], v150 offset:2048
	ds_read_b128 v[150:153], v150 offset:3072
	ds_read_b128 v[154:157], v167
	ds_read_b128 v[158:161], v167 offset:1024
	ds_read_b128 v[168:171], v167 offset:2048
	ds_read_b128 v[172:175], v167 offset:3072
	s_add_u32 s28, s28, s78
	s_addc_u32 s29, s29, 0
	s_mov_b32 m0, s82
	v_lshl_add_u64 v[236:237], s[28:29], 0, v[184:185]
	ds_read_b128 v[176:179], v166 offset:32768
	ds_read_b128 v[190:193], v166 offset:33792
	ds_read_b128 v[194:197], v166 offset:34816
	ds_read_b128 v[198:201], v166 offset:35840
	ds_read_b128 v[202:205], v166 offset:36864
	ds_read_b128 v[206:209], v166 offset:37888
	ds_read_b128 v[210:213], v166 offset:38912
	ds_read_b128 v[214:217], v166 offset:39936
	global_load_lds_dwordx4 v[236:237], off
	s_mov_b32 m0, s83
	v_lshl_add_u64 v[236:237], s[28:29], 0, v[144:145]
	global_load_lds_dwordx4 v[236:237], off
	s_waitcnt vmcnt(8) lgkmcnt(0)
	s_barrier
	s_setprio 1
	v_mfma_f32_16x16x32_bf16 v[128:131], v[132:135], v[176:179], v[128:131]
	v_mfma_f32_16x16x32_bf16 v[124:127], v[140:143], v[176:179], v[124:127]
	v_mfma_f32_16x16x32_bf16 v[112:115], v[132:135], v[194:197], v[112:115]
	v_mfma_f32_16x16x32_bf16 v[108:111], v[140:143], v[194:197], v[108:111]
	v_mfma_f32_16x16x32_bf16 v[96:99], v[132:135], v[202:205], v[96:99]
	v_mfma_f32_16x16x32_bf16 v[92:95], v[140:143], v[202:205], v[92:95]
	v_mfma_f32_16x16x32_bf16 v[80:83], v[132:135], v[210:213], v[80:83]
	v_mfma_f32_16x16x32_bf16 v[76:79], v[140:143], v[210:213], v[76:79]
	v_mfma_f32_16x16x32_bf16 v[128:131], v[136:139], v[190:193], v[128:131]
	v_mfma_f32_16x16x32_bf16 v[124:127], v[150:153], v[190:193], v[124:127]
	v_mfma_f32_16x16x32_bf16 v[112:115], v[136:139], v[198:201], v[112:115]
	v_mfma_f32_16x16x32_bf16 v[108:111], v[150:153], v[198:201], v[108:111]
	v_mfma_f32_16x16x32_bf16 v[96:99], v[136:139], v[206:209], v[96:99]
	v_mfma_f32_16x16x32_bf16 v[92:95], v[150:153], v[206:209], v[92:95]
	v_mfma_f32_16x16x32_bf16 v[80:83], v[136:139], v[214:217], v[80:83]
	v_mfma_f32_16x16x32_bf16 v[76:79], v[150:153], v[214:217], v[76:79]
	v_mfma_f32_16x16x32_bf16 v[120:123], v[154:157], v[176:179], v[120:123]
	v_mfma_f32_16x16x32_bf16 v[116:119], v[168:171], v[176:179], v[116:119]
	v_mfma_f32_16x16x32_bf16 v[104:107], v[154:157], v[194:197], v[104:107]
	v_mfma_f32_16x16x32_bf16 v[100:103], v[168:171], v[194:197], v[100:103]
	v_mfma_f32_16x16x32_bf16 v[88:91], v[154:157], v[202:205], v[88:91]
	v_mfma_f32_16x16x32_bf16 v[84:87], v[168:171], v[202:205], v[84:87]
	v_mfma_f32_16x16x32_bf16 v[72:75], v[154:157], v[210:213], v[72:75]
	v_mfma_f32_16x16x32_bf16 v[68:71], v[168:171], v[210:213], v[68:71]
	v_mfma_f32_16x16x32_bf16 v[120:123], v[158:161], v[190:193], v[120:123]
	v_mfma_f32_16x16x32_bf16 v[116:119], v[172:175], v[190:193], v[116:119]
	v_mfma_f32_16x16x32_bf16 v[104:107], v[158:161], v[198:201], v[104:107]
	v_mfma_f32_16x16x32_bf16 v[100:103], v[172:175], v[198:201], v[100:103]
	v_mfma_f32_16x16x32_bf16 v[88:91], v[158:161], v[206:209], v[88:91]
	v_mfma_f32_16x16x32_bf16 v[84:87], v[172:175], v[206:209], v[84:87]
	v_mfma_f32_16x16x32_bf16 v[72:75], v[158:161], v[214:217], v[72:75]
	v_mfma_f32_16x16x32_bf16 v[68:71], v[172:175], v[214:217], v[68:71]
	s_setprio 0
	s_barrier
	s_add_i32 s3, s3, s56
	v_lshl_add_u64 v[162:163], v[162:163], 0, s[18:19]
	s_mov_b32 m0, s3
	ds_read_b128 v[176:179], v166 offset:49152
	ds_read_b128 v[190:193], v166 offset:50176
	ds_read_b128 v[194:197], v166 offset:51200
	ds_read_b128 v[198:201], v166 offset:52224
	ds_read_b128 v[202:205], v166 offset:53248
	ds_read_b128 v[206:209], v166 offset:54272
	ds_read_b128 v[210:213], v166 offset:55296
	ds_read_b128 v[214:217], v166 offset:56320
	global_load_lds_dwordx4 v[162:163], off
	v_lshl_add_u64 v[162:163], v[218:219], 0, s[18:19]
	s_add_i32 m0, s3, 0x2000
	s_add_i32 s3, s24, s56
	global_load_lds_dwordx4 v[162:163], off
	s_mov_b32 m0, s3
	v_lshl_add_u64 v[162:163], v[228:229], 0, s[18:19]
	global_load_lds_dwordx4 v[162:163], off
	s_add_i32 m0, s3, 0x2000
	v_lshl_add_u64 v[162:163], v[230:231], 0, s[18:19]
	global_load_lds_dwordx4 v[162:163], off
	s_mov_b32 m0, s23
	v_lshl_add_u64 v[162:163], v[232:233], 0, s[18:19]
	global_load_lds_dwordx4 v[162:163], off
	s_mov_b32 m0, s62
	v_lshl_add_u64 v[162:163], v[234:235], 0, s[18:19]
	global_load_lds_dwordx4 v[162:163], off
	s_waitcnt vmcnt(8) lgkmcnt(0)
	s_barrier
	s_setprio 1
	v_mfma_f32_16x16x32_bf16 v[62:65], v[132:135], v[176:179], v[62:65]
	v_mfma_f32_16x16x32_bf16 v[58:61], v[140:143], v[176:179], v[58:61]
	v_mfma_f32_16x16x32_bf16 v[46:49], v[132:135], v[194:197], v[46:49]
	v_mfma_f32_16x16x32_bf16 v[42:45], v[140:143], v[194:197], v[42:45]
	v_mfma_f32_16x16x32_bf16 v[30:33], v[132:135], v[202:205], v[30:33]
	v_mfma_f32_16x16x32_bf16 v[26:29], v[140:143], v[202:205], v[26:29]
	v_mfma_f32_16x16x32_bf16 v[14:17], v[132:135], v[210:213], v[14:17]
	v_mfma_f32_16x16x32_bf16 v[10:13], v[140:143], v[210:213], v[10:13]
	v_mfma_f32_16x16x32_bf16 v[62:65], v[136:139], v[190:193], v[62:65]
	v_mfma_f32_16x16x32_bf16 v[58:61], v[150:153], v[190:193], v[58:61]
	v_mfma_f32_16x16x32_bf16 v[46:49], v[136:139], v[198:201], v[46:49]
	v_mfma_f32_16x16x32_bf16 v[42:45], v[150:153], v[198:201], v[42:45]
	v_mfma_f32_16x16x32_bf16 v[30:33], v[136:139], v[206:209], v[30:33]
	v_mfma_f32_16x16x32_bf16 v[26:29], v[150:153], v[206:209], v[26:29]
	v_mfma_f32_16x16x32_bf16 v[14:17], v[136:139], v[214:217], v[14:17]
	v_mfma_f32_16x16x32_bf16 v[10:13], v[150:153], v[214:217], v[10:13]
	v_mfma_f32_16x16x32_bf16 v[54:57], v[154:157], v[176:179], v[54:57]
	v_mfma_f32_16x16x32_bf16 v[50:53], v[168:171], v[176:179], v[50:53]
	v_mfma_f32_16x16x32_bf16 v[38:41], v[154:157], v[194:197], v[38:41]
	v_mfma_f32_16x16x32_bf16 v[34:37], v[168:171], v[194:197], v[34:37]
	v_mfma_f32_16x16x32_bf16 v[22:25], v[154:157], v[202:205], v[22:25]
	v_mfma_f32_16x16x32_bf16 v[18:21], v[168:171], v[202:205], v[18:21]
	v_mfma_f32_16x16x32_bf16 v[6:9], v[154:157], v[210:213], v[6:9]
	v_mfma_f32_16x16x32_bf16 v[2:5], v[168:171], v[210:213], v[2:5]
	v_mfma_f32_16x16x32_bf16 v[54:57], v[158:161], v[190:193], v[54:57]
	v_mfma_f32_16x16x32_bf16 v[50:53], v[172:175], v[190:193], v[50:53]
	v_mfma_f32_16x16x32_bf16 v[38:41], v[158:161], v[198:201], v[38:41]
	v_mfma_f32_16x16x32_bf16 v[34:37], v[172:175], v[198:201], v[34:37]
	v_mfma_f32_16x16x32_bf16 v[22:25], v[158:161], v[206:209], v[22:25]
	v_mfma_f32_16x16x32_bf16 v[18:21], v[172:175], v[206:209], v[18:21]
	v_mfma_f32_16x16x32_bf16 v[6:9], v[158:161], v[214:217], v[6:9]
	v_mfma_f32_16x16x32_bf16 v[2:5], v[172:175], v[214:217], v[2:5]
	s_setprio 0
	s_barrier
	s_add_u32 s4, s4, 0x100
	s_addc_u32 s5, s5, 0
	s_add_u32 s34, s34, 0x100
	s_addc_u32 s35, s35, 0
	s_cmp_ge_i32 s47, s42
	s_mov_b32 s24, s47
	s_cbranch_scc0 .LBB0_290
	s_and_b64 vcc, exec, s[94:95]
	s_cbranch_vccz .LBB0_293

.LBB0_436:
	s_add_u32 s30, s28, 0xfffc0080
	s_addc_u32 s31, s29, -1
	s_add_i32 s46, 0, 0x10000
	s_cmp_eq_u32 s56, 12
	s_cselect_b32 s35, s21, s31
	s_cselect_b32 s34, s51, s30
	v_add_u32_e32 v149, s46, v147
	s_cselect_b32 s31, s7, s55
	s_cselect_b32 s30, s53, s54
	s_add_i32 s58, 0, 0x14000
	ds_read_b128 v[142:145], v149
	ds_read_b128 v[150:153], v149 offset:1024
	ds_read_b128 v[154:157], v149 offset:2048
	ds_read_b128 v[158:161], v149 offset:3072
	v_add_u32_e32 v149, s58, v147
	ds_read_b128 v[162:165], v149
	ds_read_b128 v[166:169], v149 offset:1024
	ds_read_b128 v[170:173], v149 offset:2048
	ds_read_b128 v[174:177], v149 offset:3072
	v_lshl_add_u64 v[178:179], s[28:29], 0, v[138:139]
	s_add_i32 m0, s5, 0xc000
	ds_read_b128 v[190:193], v148
	ds_read_b128 v[194:197], v148 offset:1024
	ds_read_b128 v[198:201], v148 offset:2048
	ds_read_b128 v[202:205], v148 offset:3072
	ds_read_b128 v[206:209], v148 offset:4096
	ds_read_b128 v[210:213], v148 offset:5120
	ds_read_b128 v[214:217], v148 offset:6144
	ds_read_b128 v[228:231], v148 offset:7168
	global_load_lds_dwordx4 v[178:179], off
	s_add_i32 m0, s5, 0xe000
	v_lshl_add_u64 v[178:179], s[28:29], 0, v[140:141]
	global_load_lds_dwordx4 v[178:179], off
	s_waitcnt vmcnt(8) lgkmcnt(0)
	s_barrier
	s_setprio 1
	v_mfma_f32_16x16x32_bf16 v[128:131], v[142:145], v[190:193], v[128:131]
	v_mfma_f32_16x16x32_bf16 v[120:123], v[154:157], v[190:193], v[120:123]
	v_mfma_f32_16x16x32_bf16 v[112:115], v[142:145], v[198:201], v[112:115]
	v_mfma_f32_16x16x32_bf16 v[104:107], v[154:157], v[198:201], v[104:107]
	v_mfma_f32_16x16x32_bf16 v[96:99], v[142:145], v[206:209], v[96:99]
	v_mfma_f32_16x16x32_bf16 v[88:91], v[154:157], v[206:209], v[88:91]
	v_mfma_f32_16x16x32_bf16 v[80:83], v[142:145], v[214:217], v[80:83]
	v_mfma_f32_16x16x32_bf16 v[72:75], v[154:157], v[214:217], v[72:75]
	v_mfma_f32_16x16x32_bf16 v[128:131], v[150:153], v[194:197], v[128:131]
	v_mfma_f32_16x16x32_bf16 v[120:123], v[158:161], v[194:197], v[120:123]
	v_mfma_f32_16x16x32_bf16 v[112:115], v[150:153], v[202:205], v[112:115]
	v_mfma_f32_16x16x32_bf16 v[104:107], v[158:161], v[202:205], v[104:107]
	v_mfma_f32_16x16x32_bf16 v[96:99], v[150:153], v[210:213], v[96:99]
	v_mfma_f32_16x16x32_bf16 v[88:91], v[158:161], v[210:213], v[88:91]
	v_mfma_f32_16x16x32_bf16 v[80:83], v[150:153], v[228:231], v[80:83]
	v_mfma_f32_16x16x32_bf16 v[72:75], v[158:161], v[228:231], v[72:75]
	v_mfma_f32_16x16x32_bf16 v[124:127], v[162:165], v[190:193], v[124:127]
	v_mfma_f32_16x16x32_bf16 v[116:119], v[170:173], v[190:193], v[116:119]
	v_mfma_f32_16x16x32_bf16 v[108:111], v[162:165], v[198:201], v[108:111]
	v_mfma_f32_16x16x32_bf16 v[100:103], v[170:173], v[198:201], v[100:103]
	v_mfma_f32_16x16x32_bf16 v[92:95], v[162:165], v[206:209], v[92:95]
	v_mfma_f32_16x16x32_bf16 v[84:87], v[170:173], v[206:209], v[84:87]
	v_mfma_f32_16x16x32_bf16 v[76:79], v[162:165], v[214:217], v[76:79]
	v_mfma_f32_16x16x32_bf16 v[68:71], v[170:173], v[214:217], v[68:71]
	v_mfma_f32_16x16x32_bf16 v[124:127], v[166:169], v[194:197], v[124:127]
	v_mfma_f32_16x16x32_bf16 v[116:119], v[174:177], v[194:197], v[116:119]
	v_mfma_f32_16x16x32_bf16 v[108:111], v[166:169], v[202:205], v[108:111]
	v_mfma_f32_16x16x32_bf16 v[100:103], v[174:177], v[202:205], v[100:103]
	v_mfma_f32_16x16x32_bf16 v[92:95], v[166:169], v[210:213], v[92:95]
	v_mfma_f32_16x16x32_bf16 v[84:87], v[174:177], v[210:213], v[84:87]
	v_mfma_f32_16x16x32_bf16 v[76:79], v[166:169], v[228:231], v[76:79]
	v_mfma_f32_16x16x32_bf16 v[68:71], v[174:177], v[228:231], v[68:71]
	s_setprio 0
	s_barrier
	s_add_i32 s46, s46, s16
	v_lshl_add_u64 v[178:179], s[30:31], 0, v[184:185]
	s_mov_b32 m0, s46
	ds_read_b128 v[190:193], v148 offset:16384
	ds_read_b128 v[194:197], v148 offset:17408
	ds_read_b128 v[198:201], v148 offset:18432
	ds_read_b128 v[202:205], v148 offset:19456
	ds_read_b128 v[206:209], v148 offset:20480
	ds_read_b128 v[210:213], v148 offset:21504
	ds_read_b128 v[214:217], v148 offset:22528
	ds_read_b128 v[228:231], v148 offset:23552
	global_load_lds_dwordx4 v[178:179], off
	s_add_i32 m0, s46, 0x2000
	s_add_u32 s46, s30, 0x40000
	v_lshl_add_u64 v[218:219], s[30:31], 0, v[132:133]
	s_addc_u32 s47, s31, 0
	s_add_i32 s58, s58, s16
	global_load_lds_dwordx4 v[218:219], off
	v_lshl_add_u64 v[232:233], s[46:47], 0, v[184:185]
	s_mov_b32 m0, s58
	v_lshl_add_u64 v[234:235], s[34:35], 0, v[134:135]
	global_load_lds_dwordx4 v[232:233], off
	s_add_i32 m0, s58, 0x2000
	v_lshl_add_u64 v[232:233], s[46:47], 0, v[132:133]
	global_load_lds_dwordx4 v[232:233], off
	s_mov_b32 m0, s5
	v_lshl_add_u64 v[232:233], s[34:35], 0, v[136:137]
	global_load_lds_dwordx4 v[232:233], off
	s_mov_b32 m0, s23
	s_nop 0
	global_load_lds_dwordx4 v[234:235], off
	s_waitcnt vmcnt(8) lgkmcnt(0)
	s_barrier
	s_setprio 1
	v_mfma_f32_16x16x32_bf16 v[62:65], v[142:145], v[190:193], v[62:65]
	v_mfma_f32_16x16x32_bf16 v[54:57], v[154:157], v[190:193], v[54:57]
	v_mfma_f32_16x16x32_bf16 v[46:49], v[142:145], v[198:201], v[46:49]
	v_mfma_f32_16x16x32_bf16 v[38:41], v[154:157], v[198:201], v[38:41]
	v_mfma_f32_16x16x32_bf16 v[30:33], v[142:145], v[206:209], v[30:33]
	v_mfma_f32_16x16x32_bf16 v[22:25], v[154:157], v[206:209], v[22:25]
	v_mfma_f32_16x16x32_bf16 v[14:17], v[142:145], v[214:217], v[14:17]
	v_mfma_f32_16x16x32_bf16 v[6:9], v[154:157], v[214:217], v[6:9]
	v_mfma_f32_16x16x32_bf16 v[62:65], v[150:153], v[194:197], v[62:65]
	v_mfma_f32_16x16x32_bf16 v[54:57], v[158:161], v[194:197], v[54:57]
	v_mfma_f32_16x16x32_bf16 v[46:49], v[150:153], v[202:205], v[46:49]
	v_mfma_f32_16x16x32_bf16 v[38:41], v[158:161], v[202:205], v[38:41]
	v_mfma_f32_16x16x32_bf16 v[30:33], v[150:153], v[210:213], v[30:33]
	v_mfma_f32_16x16x32_bf16 v[22:25], v[158:161], v[210:213], v[22:25]
	v_mfma_f32_16x16x32_bf16 v[14:17], v[150:153], v[228:231], v[14:17]
	v_mfma_f32_16x16x32_bf16 v[6:9], v[158:161], v[228:231], v[6:9]
	v_mfma_f32_16x16x32_bf16 v[58:61], v[162:165], v[190:193], v[58:61]
	v_mfma_f32_16x16x32_bf16 v[50:53], v[170:173], v[190:193], v[50:53]
	v_mfma_f32_16x16x32_bf16 v[42:45], v[162:165], v[198:201], v[42:45]
	v_mfma_f32_16x16x32_bf16 v[34:37], v[170:173], v[198:201], v[34:37]
	v_mfma_f32_16x16x32_bf16 v[26:29], v[162:165], v[206:209], v[26:29]
	v_mfma_f32_16x16x32_bf16 v[18:21], v[170:173], v[206:209], v[18:21]
	v_mfma_f32_16x16x32_bf16 v[10:13], v[162:165], v[214:217], v[10:13]
	v_mfma_f32_16x16x32_bf16 v[2:5], v[170:173], v[214:217], v[2:5]
	v_mfma_f32_16x16x32_bf16 v[58:61], v[166:169], v[194:197], v[58:61]
	v_mfma_f32_16x16x32_bf16 v[50:53], v[174:177], v[194:197], v[50:53]
	v_mfma_f32_16x16x32_bf16 v[42:45], v[166:169], v[202:205], v[42:45]
	v_mfma_f32_16x16x32_bf16 v[34:37], v[174:177], v[202:205], v[34:37]
	v_mfma_f32_16x16x32_bf16 v[26:29], v[166:169], v[210:213], v[26:29]
	v_mfma_f32_16x16x32_bf16 v[18:21], v[174:177], v[210:213], v[18:21]
	v_mfma_f32_16x16x32_bf16 v[10:13], v[166:169], v[228:231], v[10:13]
	v_mfma_f32_16x16x32_bf16 v[2:5], v[174:177], v[228:231], v[2:5]
	s_setprio 0
	s_barrier
	s_add_i32 s46, 0, 0x18000
	v_add_u32_e32 v149, s46, v147
	s_add_i32 s47, 0, 0x1c000
	ds_read_b128 v[142:145], v149
	ds_read_b128 v[150:153], v149 offset:1024
	ds_read_b128 v[154:157], v149 offset:2048
	ds_read_b128 v[158:161], v149 offset:3072
	v_add_u32_e32 v149, s47, v147
	ds_read_b128 v[162:165], v149
	ds_read_b128 v[166:169], v149 offset:1024
	ds_read_b128 v[170:173], v149 offset:2048
	ds_read_b128 v[174:177], v149 offset:3072
	s_add_u32 s34, s34, 0x40000
	s_addc_u32 s35, s35, 0
	s_mov_b32 m0, s24
	v_lshl_add_u64 v[236:237], s[34:35], 0, v[136:137]
	ds_read_b128 v[190:193], v148 offset:32768
	ds_read_b128 v[194:197], v148 offset:33792
	ds_read_b128 v[198:201], v148 offset:34816
	ds_read_b128 v[202:205], v148 offset:35840
	ds_read_b128 v[206:209], v148 offset:36864
	ds_read_b128 v[210:213], v148 offset:37888
	ds_read_b128 v[214:217], v148 offset:38912
	ds_read_b128 v[228:231], v148 offset:39936
	global_load_lds_dwordx4 v[236:237], off
	s_mov_b32 m0, s25
	v_lshl_add_u64 v[236:237], s[34:35], 0, v[134:135]
	global_load_lds_dwordx4 v[236:237], off
	s_waitcnt vmcnt(8) lgkmcnt(0)
	s_barrier
	s_setprio 1
	v_mfma_f32_16x16x32_bf16 v[128:131], v[142:145], v[190:193], v[128:131]
	v_mfma_f32_16x16x32_bf16 v[120:123], v[154:157], v[190:193], v[120:123]
	v_mfma_f32_16x16x32_bf16 v[112:115], v[142:145], v[198:201], v[112:115]
	v_mfma_f32_16x16x32_bf16 v[104:107], v[154:157], v[198:201], v[104:107]
	v_mfma_f32_16x16x32_bf16 v[96:99], v[142:145], v[206:209], v[96:99]
	v_mfma_f32_16x16x32_bf16 v[88:91], v[154:157], v[206:209], v[88:91]
	v_mfma_f32_16x16x32_bf16 v[80:83], v[142:145], v[214:217], v[80:83]
	v_mfma_f32_16x16x32_bf16 v[72:75], v[154:157], v[214:217], v[72:75]
	v_mfma_f32_16x16x32_bf16 v[128:131], v[150:153], v[194:197], v[128:131]
	v_mfma_f32_16x16x32_bf16 v[120:123], v[158:161], v[194:197], v[120:123]
	v_mfma_f32_16x16x32_bf16 v[112:115], v[150:153], v[202:205], v[112:115]
	v_mfma_f32_16x16x32_bf16 v[104:107], v[158:161], v[202:205], v[104:107]
	v_mfma_f32_16x16x32_bf16 v[96:99], v[150:153], v[210:213], v[96:99]
	v_mfma_f32_16x16x32_bf16 v[88:91], v[158:161], v[210:213], v[88:91]
	v_mfma_f32_16x16x32_bf16 v[80:83], v[150:153], v[228:231], v[80:83]
	v_mfma_f32_16x16x32_bf16 v[72:75], v[158:161], v[228:231], v[72:75]
	v_mfma_f32_16x16x32_bf16 v[124:127], v[162:165], v[190:193], v[124:127]
	v_mfma_f32_16x16x32_bf16 v[116:119], v[170:173], v[190:193], v[116:119]
	v_mfma_f32_16x16x32_bf16 v[108:111], v[162:165], v[198:201], v[108:111]
	v_mfma_f32_16x16x32_bf16 v[100:103], v[170:173], v[198:201], v[100:103]
	v_mfma_f32_16x16x32_bf16 v[92:95], v[162:165], v[206:209], v[92:95]
	v_mfma_f32_16x16x32_bf16 v[84:87], v[170:173], v[206:209], v[84:87]
	v_mfma_f32_16x16x32_bf16 v[76:79], v[162:165], v[214:217], v[76:79]
	v_mfma_f32_16x16x32_bf16 v[68:71], v[170:173], v[214:217], v[68:71]
	v_mfma_f32_16x16x32_bf16 v[124:127], v[166:169], v[194:197], v[124:127]
	v_mfma_f32_16x16x32_bf16 v[116:119], v[174:177], v[194:197], v[116:119]
	v_mfma_f32_16x16x32_bf16 v[108:111], v[166:169], v[202:205], v[108:111]
	v_mfma_f32_16x16x32_bf16 v[100:103], v[174:177], v[202:205], v[100:103]
	v_mfma_f32_16x16x32_bf16 v[92:95], v[166:169], v[210:213], v[92:95]
	v_mfma_f32_16x16x32_bf16 v[84:87], v[174:177], v[210:213], v[84:87]
	v_mfma_f32_16x16x32_bf16 v[76:79], v[166:169], v[228:231], v[76:79]
	v_mfma_f32_16x16x32_bf16 v[68:71], v[174:177], v[228:231], v[68:71]
	s_setprio 0
	s_barrier
	s_add_i32 s34, s46, s16
	v_lshl_add_u64 v[178:179], v[178:179], 0, s[18:19]
	s_mov_b32 m0, s34
	ds_read_b128 v[190:193], v148 offset:49152
	ds_read_b128 v[194:197], v148 offset:50176
	ds_read_b128 v[198:201], v148 offset:51200
	ds_read_b128 v[202:205], v148 offset:52224
	ds_read_b128 v[206:209], v148 offset:53248
	ds_read_b128 v[210:213], v148 offset:54272
	ds_read_b128 v[214:217], v148 offset:55296
	ds_read_b128 v[228:231], v148 offset:56320
	global_load_lds_dwordx4 v[178:179], off
	s_add_i32 m0, s34, 0x2000
	s_add_u32 s30, s30, 0x40080
	v_lshl_add_u64 v[178:179], v[218:219], 0, s[18:19]
	s_addc_u32 s31, s31, 0
	s_add_i32 s34, s47, s16
	global_load_lds_dwordx4 v[178:179], off
	s_mov_b32 m0, s34
	v_lshl_add_u64 v[178:179], s[30:31], 0, v[184:185]
	global_load_lds_dwordx4 v[178:179], off
	s_add_i32 m0, s34, 0x2000
	v_lshl_add_u64 v[178:179], s[30:31], 0, v[132:133]
	global_load_lds_dwordx4 v[178:179], off
	s_mov_b32 m0, s42
	v_lshl_add_u64 v[178:179], v[232:233], 0, s[18:19]
	global_load_lds_dwordx4 v[178:179], off
	s_mov_b32 m0, s43
	v_lshl_add_u64 v[178:179], v[234:235], 0, s[18:19]
	global_load_lds_dwordx4 v[178:179], off
	s_waitcnt vmcnt(8) lgkmcnt(0)
	s_barrier
	s_setprio 1
	v_mfma_f32_16x16x32_bf16 v[62:65], v[142:145], v[190:193], v[62:65]
	v_mfma_f32_16x16x32_bf16 v[54:57], v[154:157], v[190:193], v[54:57]
	v_mfma_f32_16x16x32_bf16 v[46:49], v[142:145], v[198:201], v[46:49]
	v_mfma_f32_16x16x32_bf16 v[38:41], v[154:157], v[198:201], v[38:41]
	v_mfma_f32_16x16x32_bf16 v[30:33], v[142:145], v[206:209], v[30:33]
	v_mfma_f32_16x16x32_bf16 v[22:25], v[154:157], v[206:209], v[22:25]
	v_mfma_f32_16x16x32_bf16 v[14:17], v[142:145], v[214:217], v[14:17]
	v_mfma_f32_16x16x32_bf16 v[6:9], v[154:157], v[214:217], v[6:9]
	v_mfma_f32_16x16x32_bf16 v[62:65], v[150:153], v[194:197], v[62:65]
	v_mfma_f32_16x16x32_bf16 v[54:57], v[158:161], v[194:197], v[54:57]
	v_mfma_f32_16x16x32_bf16 v[46:49], v[150:153], v[202:205], v[46:49]
	v_mfma_f32_16x16x32_bf16 v[38:41], v[158:161], v[202:205], v[38:41]
	v_mfma_f32_16x16x32_bf16 v[30:33], v[150:153], v[210:213], v[30:33]
	v_mfma_f32_16x16x32_bf16 v[22:25], v[158:161], v[210:213], v[22:25]
	v_mfma_f32_16x16x32_bf16 v[14:17], v[150:153], v[228:231], v[14:17]
	v_mfma_f32_16x16x32_bf16 v[6:9], v[158:161], v[228:231], v[6:9]
	v_mfma_f32_16x16x32_bf16 v[58:61], v[162:165], v[190:193], v[58:61]
	v_mfma_f32_16x16x32_bf16 v[50:53], v[170:173], v[190:193], v[50:53]
	v_mfma_f32_16x16x32_bf16 v[42:45], v[162:165], v[198:201], v[42:45]
	v_mfma_f32_16x16x32_bf16 v[34:37], v[170:173], v[198:201], v[34:37]
	v_mfma_f32_16x16x32_bf16 v[26:29], v[162:165], v[206:209], v[26:29]
	v_mfma_f32_16x16x32_bf16 v[18:21], v[170:173], v[206:209], v[18:21]
	v_mfma_f32_16x16x32_bf16 v[10:13], v[162:165], v[214:217], v[10:13]
	v_mfma_f32_16x16x32_bf16 v[2:5], v[170:173], v[214:217], v[2:5]
	v_mfma_f32_16x16x32_bf16 v[58:61], v[166:169], v[194:197], v[58:61]
	v_mfma_f32_16x16x32_bf16 v[50:53], v[174:177], v[194:197], v[50:53]
	v_mfma_f32_16x16x32_bf16 v[42:45], v[166:169], v[202:205], v[42:45]
	v_mfma_f32_16x16x32_bf16 v[34:37], v[174:177], v[202:205], v[34:37]
	v_mfma_f32_16x16x32_bf16 v[26:29], v[166:169], v[210:213], v[26:29]
	v_mfma_f32_16x16x32_bf16 v[18:21], v[174:177], v[210:213], v[18:21]
	v_mfma_f32_16x16x32_bf16 v[10:13], v[166:169], v[228:231], v[10:13]
	v_mfma_f32_16x16x32_bf16 v[2:5], v[174:177], v[228:231], v[2:5]
	s_setprio 0
	s_barrier
	s_add_i32 s56, s56, 2
	s_add_u32 s28, s28, 0x100
	s_addc_u32 s29, s29, 0
	s_add_u32 s54, s54, 0x100
	s_addc_u32 s55, s55, 0
	s_cmp_gt_u32 s56, 13
	s_cbranch_scc0 .LBB0_436
	v_mul_f32_e32 v152, 0xbfb8aa3b, v128
	v_mul_f32_e32 v153, 0xbfb8aa3b, v129
	v_exp_f32_e32 v152, v152
	v_exp_f32_e32 v153, v153
	s_lshl_b32 s4, s4, 8
	s_lshl_b32 s7, s50, 7
	v_add_f32_e32 v152, 1.0, v152
	v_add_f32_e32 v153, 1.0, v153
	v_rcp_f32_e32 v152, v152
	v_rcp_f32_e32 v153, v153
	v_mov_b32_e32 v142, v67
	v_mov_b32_e32 v143, v146
	s_or_b32 s7, s7, s41
	v_pk_mul_f32 v[128:129], v[128:129], v[152:153]
	s_add_i32 s4, s4, s40
	v_pk_mul_f32 v[124:125], v[128:129], v[124:125]
	s_and_b64 vcc, exec, s[38:39]
	v_cvt_pk_bf16_f32 v124, v124, v125
	v_mul_f32_e32 v125, 0xbfb8aa3b, v130
	v_exp_f32_e32 v125, v125
	v_lshl_add_u32 v144, v143, 3, s7
	v_add_u32_e32 v149, s4, v142
	v_ashrrev_i32_e32 v145, 31, v144
	v_add_f32_e32 v125, 1.0, v125
	v_rcp_f32_e32 v128, v125
	v_mul_f32_e32 v125, 0xbfb8aa3b, v131
	v_exp_f32_e32 v125, v125
	v_mov_b64_e32 v[142:143], s[80:81]
	v_mad_i64_i32 v[150:151], s[28:29], v149, s59, v[142:143]
	v_add_f32_e32 v125, 1.0, v125
	v_rcp_f32_e32 v129, v125
	v_lshlrev_b64 v[144:145], 1, v[144:145]
	v_lshl_add_u64 v[150:151], v[150:151], 0, v[144:145]
	s_mov_b32 s50, s6
	v_pk_mul_f32 v[128:129], v[130:131], v[128:129]
	s_mov_b32 s4, s20
	v_pk_mul_f32 v[126:127], v[128:129], v[126:127]
	s_mov_b64 s[30:31], s[36:37]
	v_cvt_pk_bf16_f32 v125, v126, v127
	v_mul_f32_e32 v126, 0xbfb8aa3b, v120
	v_mul_f32_e32 v127, 0xbfb8aa3b, v121
	v_exp_f32_e32 v126, v126
	v_exp_f32_e32 v127, v127
	v_add_f32_e32 v126, 1.0, v126
	v_add_f32_e32 v127, 1.0, v127
	v_rcp_f32_e32 v126, v126
	v_rcp_f32_e32 v127, v127
	s_nop 0
	v_pk_mul_f32 v[120:121], v[120:121], v[126:127]
	s_nop 0
	v_pk_mul_f32 v[116:117], v[120:121], v[116:117]
	s_nop 0
	v_cvt_pk_bf16_f32 v126, v116, v117
	v_mul_f32_e32 v116, 0xbfb8aa3b, v122
	v_mul_f32_e32 v117, 0xbfb8aa3b, v123
	v_exp_f32_e32 v116, v116
	v_exp_f32_e32 v117, v117
	v_add_f32_e32 v116, 1.0, v116
	v_add_f32_e32 v117, 1.0, v117
	v_rcp_f32_e32 v116, v116
	v_rcp_f32_e32 v117, v117
	s_nop 0
	v_pk_mul_f32 v[116:117], v[122:123], v[116:117]
	s_nop 0
	v_pk_mul_f32 v[116:117], v[116:117], v[118:119]
	v_mul_f32_e32 v118, 0xbfb8aa3b, v112
	v_mul_f32_e32 v119, 0xbfb8aa3b, v113
	v_exp_f32_e32 v118, v118
	v_exp_f32_e32 v119, v119
	v_cvt_pk_bf16_f32 v127, v116, v117
	v_add_u32_e32 v116, 16, v149
	v_add_f32_e32 v118, 1.0, v118
	v_add_f32_e32 v119, 1.0, v119
	v_rcp_f32_e32 v118, v118
	v_rcp_f32_e32 v119, v119
	v_mad_i64_i32 v[116:117], s[28:29], v116, s59, v[142:143]
	v_lshl_add_u64 v[116:117], v[116:117], 0, v[144:145]
	v_pk_mul_f32 v[112:113], v[112:113], v[118:119]
	global_store_dwordx4 v[150:151], v[124:127], off sc1
	v_pk_mul_f32 v[108:109], v[112:113], v[108:109]
	s_nop 0
	v_cvt_pk_bf16_f32 v108, v108, v109
	v_mul_f32_e32 v109, 0xbfb8aa3b, v114
	v_exp_f32_e32 v109, v109
	s_nop 0
	v_add_f32_e32 v109, 1.0, v109
	v_rcp_f32_e32 v112, v109
	v_mul_f32_e32 v109, 0xbfb8aa3b, v115
	v_exp_f32_e32 v109, v109
	s_nop 0
	v_add_f32_e32 v109, 1.0, v109
	v_rcp_f32_e32 v113, v109
	s_nop 0
	v_pk_mul_f32 v[112:113], v[114:115], v[112:113]
	s_nop 0
	v_pk_mul_f32 v[110:111], v[112:113], v[110:111]
	s_nop 0
	v_cvt_pk_bf16_f32 v109, v110, v111
	v_mul_f32_e32 v110, 0xbfb8aa3b, v104
	v_mul_f32_e32 v111, 0xbfb8aa3b, v105
	v_exp_f32_e32 v110, v110
	v_exp_f32_e32 v111, v111
	v_add_f32_e32 v110, 1.0, v110
	v_add_f32_e32 v111, 1.0, v111
	v_rcp_f32_e32 v110, v110
	v_rcp_f32_e32 v111, v111
	s_nop 0
	v_pk_mul_f32 v[104:105], v[104:105], v[110:111]
	s_nop 0
	v_pk_mul_f32 v[100:101], v[104:105], v[100:101]
	s_nop 0
	v_cvt_pk_bf16_f32 v110, v100, v101
	v_mul_f32_e32 v100, 0xbfb8aa3b, v106
	v_mul_f32_e32 v101, 0xbfb8aa3b, v107
	v_exp_f32_e32 v100, v100
	v_exp_f32_e32 v101, v101
	v_add_f32_e32 v100, 1.0, v100
	v_add_f32_e32 v101, 1.0, v101
	v_rcp_f32_e32 v100, v100
	v_rcp_f32_e32 v101, v101
	s_nop 0
	v_pk_mul_f32 v[100:101], v[106:107], v[100:101]
	s_nop 0
	v_pk_mul_f32 v[100:101], v[100:101], v[102:103]
	v_mul_f32_e32 v102, 0xbfb8aa3b, v96
	v_mul_f32_e32 v103, 0xbfb8aa3b, v97
	v_exp_f32_e32 v102, v102
	v_exp_f32_e32 v103, v103
	v_cvt_pk_bf16_f32 v111, v100, v101
	v_add_u32_e32 v100, 32, v149
	v_add_f32_e32 v102, 1.0, v102
	v_add_f32_e32 v103, 1.0, v103
	v_rcp_f32_e32 v102, v102
	v_rcp_f32_e32 v103, v103
	v_mad_i64_i32 v[100:101], s[28:29], v100, s59, v[142:143]
	v_lshl_add_u64 v[100:101], v[100:101], 0, v[144:145]
	v_pk_mul_f32 v[96:97], v[96:97], v[102:103]
	global_store_dwordx4 v[116:117], v[108:111], off sc1
	v_pk_mul_f32 v[92:93], v[96:97], v[92:93]
	s_nop 0
	v_cvt_pk_bf16_f32 v92, v92, v93
	v_mul_f32_e32 v93, 0xbfb8aa3b, v98
	v_exp_f32_e32 v93, v93
	s_nop 0
	v_add_f32_e32 v93, 1.0, v93
	v_rcp_f32_e32 v96, v93
	v_mul_f32_e32 v93, 0xbfb8aa3b, v99
	v_exp_f32_e32 v93, v93
	s_nop 0
	v_add_f32_e32 v93, 1.0, v93
	v_rcp_f32_e32 v97, v93
	s_nop 0
	v_pk_mul_f32 v[96:97], v[98:99], v[96:97]
	s_nop 0
	v_pk_mul_f32 v[94:95], v[96:97], v[94:95]
	s_nop 0
	v_cvt_pk_bf16_f32 v93, v94, v95
	v_mul_f32_e32 v94, 0xbfb8aa3b, v88
	v_mul_f32_e32 v95, 0xbfb8aa3b, v89
	v_exp_f32_e32 v94, v94
	v_exp_f32_e32 v95, v95
	v_add_f32_e32 v94, 1.0, v94
	v_add_f32_e32 v95, 1.0, v95
	v_rcp_f32_e32 v94, v94
	v_rcp_f32_e32 v95, v95
	s_nop 0
	v_pk_mul_f32 v[88:89], v[88:89], v[94:95]
	s_nop 0
	v_pk_mul_f32 v[84:85], v[88:89], v[84:85]
	s_nop 0
	v_cvt_pk_bf16_f32 v94, v84, v85
	v_mul_f32_e32 v84, 0xbfb8aa3b, v90
	v_mul_f32_e32 v85, 0xbfb8aa3b, v91
	v_exp_f32_e32 v84, v84
	v_exp_f32_e32 v85, v85
	v_add_f32_e32 v84, 1.0, v84
	v_add_f32_e32 v85, 1.0, v85
	v_rcp_f32_e32 v84, v84
	v_rcp_f32_e32 v85, v85
	s_nop 0
	v_pk_mul_f32 v[84:85], v[90:91], v[84:85]
	s_nop 0
	v_pk_mul_f32 v[84:85], v[84:85], v[86:87]
	v_mul_f32_e32 v86, 0xbfb8aa3b, v80
	v_mul_f32_e32 v87, 0xbfb8aa3b, v81
	v_exp_f32_e32 v86, v86
	v_exp_f32_e32 v87, v87
	v_cvt_pk_bf16_f32 v95, v84, v85
	v_add_u32_e32 v84, 48, v149
	v_add_f32_e32 v86, 1.0, v86
	v_add_f32_e32 v87, 1.0, v87
	v_rcp_f32_e32 v86, v86
	v_rcp_f32_e32 v87, v87
	v_mad_i64_i32 v[84:85], s[28:29], v84, s59, v[142:143]
	v_lshl_add_u64 v[84:85], v[84:85], 0, v[144:145]
	v_pk_mul_f32 v[80:81], v[80:81], v[86:87]
	global_store_dwordx4 v[100:101], v[92:95], off sc1
	v_pk_mul_f32 v[76:77], v[80:81], v[76:77]
	s_nop 0
	v_cvt_pk_bf16_f32 v76, v76, v77
	v_mul_f32_e32 v77, 0xbfb8aa3b, v82
	v_exp_f32_e32 v77, v77
	s_nop 0
	v_add_f32_e32 v77, 1.0, v77
	v_rcp_f32_e32 v80, v77
	v_mul_f32_e32 v77, 0xbfb8aa3b, v83
	v_exp_f32_e32 v77, v77
	s_nop 0
	v_add_f32_e32 v77, 1.0, v77
	v_rcp_f32_e32 v81, v77
	s_nop 0
	v_pk_mul_f32 v[80:81], v[82:83], v[80:81]
	s_nop 0
	v_pk_mul_f32 v[78:79], v[80:81], v[78:79]
	s_nop 0
	v_cvt_pk_bf16_f32 v77, v78, v79
	v_mul_f32_e32 v78, 0xbfb8aa3b, v72
	v_mul_f32_e32 v79, 0xbfb8aa3b, v73
	v_exp_f32_e32 v78, v78
	v_exp_f32_e32 v79, v79
	v_add_f32_e32 v78, 1.0, v78
	v_add_f32_e32 v79, 1.0, v79
	v_rcp_f32_e32 v78, v78
	v_rcp_f32_e32 v79, v79
	s_nop 0
	v_pk_mul_f32 v[72:73], v[72:73], v[78:79]
	s_nop 0
	v_pk_mul_f32 v[68:69], v[72:73], v[68:69]
	s_nop 0
	v_cvt_pk_bf16_f32 v78, v68, v69
	v_mul_f32_e32 v68, 0xbfb8aa3b, v74
	v_mul_f32_e32 v69, 0xbfb8aa3b, v75
	v_exp_f32_e32 v68, v68
	v_exp_f32_e32 v69, v69
	v_add_f32_e32 v68, 1.0, v68
	v_add_f32_e32 v69, 1.0, v69
	v_rcp_f32_e32 v68, v68
	v_rcp_f32_e32 v69, v69
	s_nop 0
	v_pk_mul_f32 v[68:69], v[74:75], v[68:69]
	s_nop 0
	v_pk_mul_f32 v[68:69], v[68:69], v[70:71]
	v_mul_f32_e32 v70, 0xbfb8aa3b, v62
	v_mul_f32_e32 v71, 0xbfb8aa3b, v63
	v_exp_f32_e32 v70, v70
	v_exp_f32_e32 v71, v71
	v_cvt_pk_bf16_f32 v79, v68, v69
	v_add_u32_e32 v68, 0x80, v149
	v_add_f32_e32 v70, 1.0, v70
	v_add_f32_e32 v71, 1.0, v71
	v_rcp_f32_e32 v70, v70
	v_rcp_f32_e32 v71, v71
	v_mad_i64_i32 v[68:69], s[28:29], v68, s59, v[142:143]
	v_lshl_add_u64 v[68:69], v[68:69], 0, v[144:145]
	v_pk_mul_f32 v[62:63], v[62:63], v[70:71]
	global_store_dwordx4 v[84:85], v[76:79], off sc1
	v_pk_mul_f32 v[58:59], v[62:63], v[58:59]
	s_nop 0
	v_cvt_pk_bf16_f32 v58, v58, v59
	v_mul_f32_e32 v59, 0xbfb8aa3b, v64
	v_exp_f32_e32 v59, v59
	s_nop 0
	v_add_f32_e32 v59, 1.0, v59
	v_rcp_f32_e32 v62, v59
	v_mul_f32_e32 v59, 0xbfb8aa3b, v65
	v_exp_f32_e32 v59, v59
	s_nop 0
	v_add_f32_e32 v59, 1.0, v59
	v_rcp_f32_e32 v63, v59
	s_nop 0
	v_pk_mul_f32 v[62:63], v[64:65], v[62:63]
	s_nop 0
	v_pk_mul_f32 v[60:61], v[62:63], v[60:61]
	s_nop 0
	v_cvt_pk_bf16_f32 v59, v60, v61
	v_mul_f32_e32 v60, 0xbfb8aa3b, v54
	v_mul_f32_e32 v61, 0xbfb8aa3b, v55
	v_exp_f32_e32 v60, v60
	v_exp_f32_e32 v61, v61
	v_add_f32_e32 v60, 1.0, v60
	v_add_f32_e32 v61, 1.0, v61
	v_rcp_f32_e32 v60, v60
	v_rcp_f32_e32 v61, v61
	s_nop 0
	v_pk_mul_f32 v[54:55], v[54:55], v[60:61]
	s_nop 0
	v_pk_mul_f32 v[50:51], v[54:55], v[50:51]
	s_nop 0
	v_cvt_pk_bf16_f32 v60, v50, v51
	v_mul_f32_e32 v50, 0xbfb8aa3b, v56
	v_mul_f32_e32 v51, 0xbfb8aa3b, v57
	v_exp_f32_e32 v50, v50
	v_exp_f32_e32 v51, v51
	v_add_f32_e32 v50, 1.0, v50
	v_add_f32_e32 v51, 1.0, v51
	v_rcp_f32_e32 v50, v50
	v_rcp_f32_e32 v51, v51
	s_nop 0
	v_pk_mul_f32 v[50:51], v[56:57], v[50:51]
	s_nop 0
	v_pk_mul_f32 v[50:51], v[50:51], v[52:53]
	v_mul_f32_e32 v52, 0xbfb8aa3b, v46
	v_mul_f32_e32 v53, 0xbfb8aa3b, v47
	v_exp_f32_e32 v52, v52
	v_exp_f32_e32 v53, v53
	v_cvt_pk_bf16_f32 v61, v50, v51
	v_add_u32_e32 v50, 0x90, v149
	v_add_f32_e32 v52, 1.0, v52
	v_add_f32_e32 v53, 1.0, v53
	v_rcp_f32_e32 v52, v52
	v_rcp_f32_e32 v53, v53
	v_mad_i64_i32 v[50:51], s[28:29], v50, s59, v[142:143]
	v_lshl_add_u64 v[50:51], v[50:51], 0, v[144:145]
	v_pk_mul_f32 v[46:47], v[46:47], v[52:53]
	global_store_dwordx4 v[68:69], v[58:61], off sc1
	v_pk_mul_f32 v[42:43], v[46:47], v[42:43]
	s_nop 0
	v_cvt_pk_bf16_f32 v42, v42, v43
	v_mul_f32_e32 v43, 0xbfb8aa3b, v48
	v_exp_f32_e32 v43, v43
	s_nop 0
	v_add_f32_e32 v43, 1.0, v43
	v_rcp_f32_e32 v46, v43
	v_mul_f32_e32 v43, 0xbfb8aa3b, v49
	v_exp_f32_e32 v43, v43
	s_nop 0
	v_add_f32_e32 v43, 1.0, v43
	v_rcp_f32_e32 v47, v43
	s_nop 0
	v_pk_mul_f32 v[46:47], v[48:49], v[46:47]
	s_nop 0
	v_pk_mul_f32 v[44:45], v[46:47], v[44:45]
	s_nop 0
	v_cvt_pk_bf16_f32 v43, v44, v45
	v_mul_f32_e32 v44, 0xbfb8aa3b, v38
	v_mul_f32_e32 v45, 0xbfb8aa3b, v39
	v_exp_f32_e32 v44, v44
	v_exp_f32_e32 v45, v45
	v_add_f32_e32 v44, 1.0, v44
	v_add_f32_e32 v45, 1.0, v45
	v_rcp_f32_e32 v44, v44
	v_rcp_f32_e32 v45, v45
	s_nop 0
	v_pk_mul_f32 v[38:39], v[38:39], v[44:45]
	s_nop 0
	v_pk_mul_f32 v[34:35], v[38:39], v[34:35]
	s_nop 0
	v_cvt_pk_bf16_f32 v44, v34, v35
	v_mul_f32_e32 v34, 0xbfb8aa3b, v40
	v_mul_f32_e32 v35, 0xbfb8aa3b, v41
	v_exp_f32_e32 v34, v34
	v_exp_f32_e32 v35, v35
	v_add_f32_e32 v34, 1.0, v34
	v_add_f32_e32 v35, 1.0, v35
	v_rcp_f32_e32 v34, v34
	v_rcp_f32_e32 v35, v35
	s_nop 0
	v_pk_mul_f32 v[34:35], v[40:41], v[34:35]
	s_nop 0
	v_pk_mul_f32 v[34:35], v[34:35], v[36:37]
	v_mul_f32_e32 v36, 0xbfb8aa3b, v30
	v_mul_f32_e32 v37, 0xbfb8aa3b, v31
	v_exp_f32_e32 v36, v36
	v_exp_f32_e32 v37, v37
	v_cvt_pk_bf16_f32 v45, v34, v35
	v_add_u32_e32 v34, 0xa0, v149
	v_add_f32_e32 v36, 1.0, v36
	v_add_f32_e32 v37, 1.0, v37
	v_rcp_f32_e32 v36, v36
	v_rcp_f32_e32 v37, v37
	v_mad_i64_i32 v[34:35], s[28:29], v34, s59, v[142:143]
	v_lshl_add_u64 v[34:35], v[34:35], 0, v[144:145]
	v_pk_mul_f32 v[30:31], v[30:31], v[36:37]
	global_store_dwordx4 v[50:51], v[42:45], off sc1
	v_pk_mul_f32 v[26:27], v[30:31], v[26:27]
	s_nop 0
	v_cvt_pk_bf16_f32 v26, v26, v27
	v_mul_f32_e32 v27, 0xbfb8aa3b, v32
	v_exp_f32_e32 v27, v27
	s_nop 0
	v_add_f32_e32 v27, 1.0, v27
	v_rcp_f32_e32 v30, v27
	v_mul_f32_e32 v27, 0xbfb8aa3b, v33
	v_exp_f32_e32 v27, v27
	s_nop 0
	v_add_f32_e32 v27, 1.0, v27
	v_rcp_f32_e32 v31, v27
	s_nop 0
	v_pk_mul_f32 v[30:31], v[32:33], v[30:31]
	s_nop 0
	v_pk_mul_f32 v[28:29], v[30:31], v[28:29]
	s_nop 0
	v_cvt_pk_bf16_f32 v27, v28, v29
	v_mul_f32_e32 v28, 0xbfb8aa3b, v22
	v_mul_f32_e32 v29, 0xbfb8aa3b, v23
	v_exp_f32_e32 v28, v28
	v_exp_f32_e32 v29, v29
	v_add_f32_e32 v28, 1.0, v28
	v_add_f32_e32 v29, 1.0, v29
	v_rcp_f32_e32 v28, v28
	v_rcp_f32_e32 v29, v29
	s_nop 0
	v_pk_mul_f32 v[22:23], v[22:23], v[28:29]
	s_nop 0
	v_pk_mul_f32 v[18:19], v[22:23], v[18:19]
	s_nop 0
	v_cvt_pk_bf16_f32 v28, v18, v19
	v_mul_f32_e32 v18, 0xbfb8aa3b, v24
	v_mul_f32_e32 v19, 0xbfb8aa3b, v25
	v_exp_f32_e32 v18, v18
	v_exp_f32_e32 v19, v19
	v_add_f32_e32 v18, 1.0, v18
	v_add_f32_e32 v19, 1.0, v19
	v_rcp_f32_e32 v18, v18
	v_rcp_f32_e32 v19, v19
	s_nop 0
	v_pk_mul_f32 v[18:19], v[24:25], v[18:19]
	s_nop 0
	v_pk_mul_f32 v[18:19], v[18:19], v[20:21]
	v_mul_f32_e32 v20, 0xbfb8aa3b, v14
	v_mul_f32_e32 v21, 0xbfb8aa3b, v15
	v_exp_f32_e32 v20, v20
	v_exp_f32_e32 v21, v21
	v_cvt_pk_bf16_f32 v29, v18, v19
	v_add_u32_e32 v18, 0xb0, v149
	v_add_f32_e32 v20, 1.0, v20
	v_add_f32_e32 v21, 1.0, v21
	v_rcp_f32_e32 v20, v20
	v_rcp_f32_e32 v21, v21
	v_mad_i64_i32 v[18:19], s[28:29], v18, s59, v[142:143]
	v_lshl_add_u64 v[18:19], v[18:19], 0, v[144:145]
	v_pk_mul_f32 v[14:15], v[14:15], v[20:21]
	s_mov_b64 s[28:29], s[26:27]
	v_pk_mul_f32 v[10:11], v[14:15], v[10:11]
	global_store_dwordx4 v[34:35], v[26:29], off sc1
	v_cvt_pk_bf16_f32 v10, v10, v11
	v_mul_f32_e32 v11, 0xbfb8aa3b, v16
	v_exp_f32_e32 v11, v11
	s_nop 0
	v_add_f32_e32 v11, 1.0, v11
	v_rcp_f32_e32 v14, v11
	v_mul_f32_e32 v11, 0xbfb8aa3b, v17
	v_exp_f32_e32 v11, v11
	s_nop 0
	v_add_f32_e32 v11, 1.0, v11
	v_rcp_f32_e32 v15, v11
	s_nop 0
	v_pk_mul_f32 v[14:15], v[16:17], v[14:15]
	s_nop 0
	v_pk_mul_f32 v[12:13], v[14:15], v[12:13]
	s_nop 0
	v_cvt_pk_bf16_f32 v11, v12, v13
	v_mul_f32_e32 v12, 0xbfb8aa3b, v6
	v_mul_f32_e32 v13, 0xbfb8aa3b, v7
	v_exp_f32_e32 v12, v12
	v_exp_f32_e32 v13, v13
	v_add_f32_e32 v12, 1.0, v12
	v_add_f32_e32 v13, 1.0, v13
	v_rcp_f32_e32 v12, v12
	v_rcp_f32_e32 v13, v13
	s_nop 0
	v_pk_mul_f32 v[6:7], v[6:7], v[12:13]
	s_nop 0
	v_pk_mul_f32 v[2:3], v[6:7], v[2:3]
	s_nop 0
	v_cvt_pk_bf16_f32 v12, v2, v3
	v_mul_f32_e32 v2, 0xbfb8aa3b, v8
	v_mul_f32_e32 v3, 0xbfb8aa3b, v9
	v_exp_f32_e32 v2, v2
	v_exp_f32_e32 v3, v3
	v_add_f32_e32 v2, 1.0, v2
	v_add_f32_e32 v3, 1.0, v3
	v_rcp_f32_e32 v2, v2
	v_rcp_f32_e32 v3, v3
	s_nop 0
	v_pk_mul_f32 v[2:3], v[8:9], v[2:3]
	s_nop 0
	v_pk_mul_f32 v[2:3], v[2:3], v[4:5]
	s_nop 0
	v_cvt_pk_bf16_f32 v13, v2, v3
	global_store_dwordx4 v[18:19], v[10:13], off sc1
	s_cbranch_vccz .LBB0_433
	s_waitcnt vmcnt(0)
	s_cmpk_gt_u32 s1, 0xff
	s_cbranch_scc1 .LBB0_440
	s_barrier
